# fox items paired per CU via HW_ID slot: first block of a CU takes from long list, second from short list
# baseline (speedup 1.0000x reference)
; DI int pop_item(int* ctr, int* slot) {
;   __syncthreads();
;   if (threadIdx.x == 0) *slot = atomicAdd(ctr, 1);
;   __syncthreads();
;   return *slot;
; __global__ void __launch_bounds__(256, 2) hybrid_fwd(Params p) {
;     ...
;         int* ctr = p.ctr + l * 2 + 1 + rep * 4;
;         for (;;) {
;           const int it = pop_item(ctr, &slot);
;           if (it >= 1024) break;
;           if (it < 512) { if (!dry || (P3_MASK & 1)) nsa_item(p, l, it, lds, dry); }
;           else { if (!dry || (P3_MASK & 2)) fox_item(p, l, it - 512, lds, dry); }
.LBB0_631:
	s_barrier
	s_and_saveexec_b64 s[0:1], s[26:27]
	s_cbranch_execz .LBB0_635
	s_mov_b64 s[4:5], exec
	v_mbcnt_lo_u32_b32 v0, s4, 0
	v_mbcnt_hi_u32_b32 v0, s5, v0
	v_cmp_eq_u32_e32 vcc, 0, v0
	s_and_saveexec_b64 s[2:3], vcc
	s_cbranch_execz .LBB0_634
	s_bcnt1_i32_b64 s4, s[4:5]
	v_mov_b32_e32 v2, s4
	v_readlane_b32 s4, v253, 36
	s_and_b32 s4, s4, 7
	s_lshl_b32 s4, s4, 4
	s_add_i32 s4, s4, 20
	v_mov_b32_e32 v4, s4
	v_readlane_b32 s4, v254, 7
	v_readlane_b32 s5, v254, 8
	s_nop 4
	global_atomic_add v2, v4, v2, s[4:5] sc0
	s_waitcnt vmcnt(0)
	v_subrev_u32_e32 v4, 64, v2
	v_cmp_gt_u32_e32 vcc, 64, v4
	s_cbranch_vccz .LBB0_634
	s_getreg_b32 s16, hwreg(HW_REG_HW_ID, 8, 8)
	s_and_b32 vcc_lo, s16, 15
	s_bfe_u32 s16, s16, 0x20005
	s_lshl_b32 s16, s16, 4
	s_or_b32 s16, s16, vcc_lo
	s_min_u32 s16, s16, 62
	s_lshl_b32 s16, s16, 2
	v_readlane_b32 vcc_lo, v253, 36
	s_and_b32 vcc_lo, vcc_lo, 7
	s_lshl_b32 vcc_lo, vcc_lo, 8
	s_add_i32 s16, s16, vcc_lo
	s_and_b32 vcc_hi, s4, 8
	s_sub_i32 s16, s16, vcc_hi
	s_add_i32 s16, s16, 0x1d04
	v_mov_b32_e32 v5, s16
	v_mov_b32_e32 v6, 1
	global_atomic_add v5, v5, v6, s[4:5] sc0
	s_add_i32 s16, vcc_lo, 0x2d04
	s_waitcnt vmcnt(0)
	v_and_b32_e32 v5, 1, v5
	v_lshlrev_b32_e32 v7, 2, v5
	v_add_u32_e32 v7, s16, v7
	global_atomic_add v3, v7, v6, s[4:5] sc0
	s_waitcnt vmcnt(0)
	v_cmp_gt_u32_e32 vcc, 32, v3
	s_cbranch_vccnz .Lfq_have
	v_xor_b32_e32 v5, 1, v5
	v_lshlrev_b32_e32 v7, 2, v5
	v_add_u32_e32 v7, s16, v7
	global_atomic_add v3, v7, v6, s[4:5] sc0
	s_waitcnt vmcnt(0)
.Lfq_have:
	v_sub_u32_e32 v7, 63, v3
	v_cmp_eq_u32_e32 vcc, 1, v5
	s_nop 1
	v_cndmask_b32_e32 v3, v3, v7, vcc
	v_add_u32_e32 v2, 64, v3
